# previous + static s_setprio 1 for waves 4-7 across the diff-attention KV loop
# speedup vs baseline: 1.0076x; 1.0051x over previous
; DEVI int v_st(int k, int c) { const int kk = (k & ~0xC) | ((k & 4) << 1) | ((k & 8) >> 1); return ((kk >> 3) * 4 + (c >> 5)) * 512 + ((kk & 7) * 32 + (c & 31)) * 2; }
; DEVI int v_rd_base(int lane) { return ((lane & 3) << 3) | (((lane >> 2) & 3) << 6) | (((lane >> 4) & 1) << 5) | (((lane >> 5) & 1) << 8); }
; #define SLOAD(k0) do { vs0 = *(const bf16x8*)(vp0 + (long)(k0) * ldv); vs1 = *(const bf16x8*)(vp0 + (long)((k0) + 32) * ldv); \
;     ksg[0] = *(const bf16x8*)(kp0 + (long)(k0) * ldk0); \
;     if constexpr (DQK == 192) { ksg[1] = *(const bf16x8*)(kp0 + (long)((k0) + 32) * ldk0); ksg[2] = *(const bf16x8*)(kp2 + (long)(k0) * ldk1); } } while (0)
; #define SWAIT() asm volatile("s_waitcnt vmcnt(0)" ::: "memory")
; template <int DQK, bool PIPE>
; DEVI void attn_body(const u16* __restrict__ Qb, int ldq, const u16* __restrict__ K0, int ldk0, const u16* __restrict__ K1, int ldk1,
;                     const u16* __restrict__ Vh, int ldv, u16* __restrict__ Ob, int ldo, int seq, float scale, char* lds) {
;     ...
;   bf16x8 qr[ND0];
;   const u16* Qw = Qb + (long)(wid * 32 + r32) * ldq + hi * 8;
; #pragma unroll
;   for (int d0 = 0; d0 < ND0; ++d0) qr[d0] = *(const bf16x8*)(Qw + d0 * 16);
;   const int sr = tid >> 4, sc = (tid & 15) * 8, vst0 = v_st(sr, sc), vst1 = v_st(32 + sr, sc);
;   const int vb0 = (int)(uintptr_t)V_lds + v_rd_base(lane);
;   bf16x8 vs0, vs1, ksg[NKC];
;   const int krow0 = (DQK == 64) ? (tid >> 3) : (tid >> 4), kchk0 = (DQK == 64) ? (tid & 7) : (tid & 15);
;   const u16* kp0 = K0 + (long)krow0 * ldk0 + kchk0 * 8;
;   const int koff0 = krow0 * KRB + ((kchk0 * 16) ^ (((krow0 >> 1) & 7) << 4));
;   const int koff1 = (krow0 + 32) * KRB + ((kchk0 * 16) ^ (((krow0 >> 1) & 7) << 4));
;   const int krow2 = tid >> 3, kchk2 = 16 + (tid & 7);
;   const u16* kp2 = K1 + (long)krow2 * ldk1 + (tid & 7) * 8;
;   const int koff2 = krow2 * KRB + ((kchk2 * 16) ^ (((krow2 >> 1) & 7) << 4));
;   const u16* vp0 = Vh + (long)sr * ldv + sc;
;     ...
;   bf16x8 pa0, pa1, pa2, pa3; const int NT = seq / 64;
;   if constexpr (PIPE) {
;     f32x16 pA0, pA1, pB0, pB1; float mnA, mnB, alA, alB;
;     SLOAD(0); SWAIT(); SWRITE(0); __syncthreads();
;     QKT(pA0, pA1, K_lds); partialSM(pA0, pA1, m_reg, mnA, alA, scale);
;     SLOAD(64);
;     SWAIT(); SWRITE(1); __syncthreads();
.LBB0_467:
	s_andn2_b64 vcc, exec, s[2:3]
	s_cbranch_vccnz .LBB0_427
	s_lshr_b32 s2, s17, 2
	s_and_b32 s2, s2, 8
	v_readlane_b32 s3, v253, 62
	s_ashr_i32 s8, s17, 6
	s_or_b32 s6, s2, s3
	s_lshl_b32 s3, s17, 8
	s_mul_i32 s2, s8, 0x2100
	s_and_b32 s3, s3, 0x1f00
	s_add_i32 s2, s2, s3
	s_ashr_i32 s3, s2, 31
	s_mul_i32 s9, s2, 0x4c00
	s_mul_hi_i32 s7, s2, 0x4c00
	s_add_u32 s9, s44, s9
	s_addc_u32 s7, s45, s7
	s_lshl_b32 s6, s6, 6
	s_and_b32 s14, s6, 0x380
	s_lshl_b32 s10, s14, 1
	s_add_u32 s6, s9, s10
	s_addc_u32 s7, s7, 0
	v_readlane_b32 s26, v254, 3
	s_add_u32 s6, s6, s26
	s_addc_u32 s7, s7, 0
	s_add_u32 s6, s6, 0x1800
	s_addc_u32 s7, s7, 0
	s_mul_i32 s11, s8, 0x9cc0000
	s_mul_hi_i32 s9, s8, 0x9cc0000
	s_add_u32 s11, s44, s11
	s_addc_u32 s9, s45, s9
	s_add_u32 s15, s11, s10
	s_addc_u32 s9, s9, 0
	s_add_u32 s10, s15, s26
	s_addc_u32 s11, s9, 0
	s_add_u32 s10, s10, 0x2000
	s_addc_u32 s11, s11, 0
	v_mov_b32_e32 v70, v208
	s_add_u32 s26, s15, 0x2800
	v_mov_b64_e32 v[0:1], s[10:11]
	s_waitcnt vmcnt(2)
	v_lshlrev_b32_e32 v63, 4, v70
	s_waitcnt vmcnt(1)
	v_ashrrev_i32_e32 v64, 3, v70
	s_addc_u32 s27, s9, 0
	v_lshlrev_b32_e32 v32, 3, v70
	v_mad_i64_i32 v[0:1], s[10:11], v64, s93, v[0:1]
	v_and_b32_e32 v48, 0x70, v63
	v_mov_b32_e32 v49, v193
	v_ashrrev_i32_e32 v62, 4, v70
	v_and_b32_e32 v2, 0x78, v32
	v_lshl_add_u64 v[12:13], v[0:1], 0, v[48:49]
	v_mov_b64_e32 v[0:1], s[26:27]
	v_mad_i64_i32 v[0:1], s[10:11], v62, s93, v[0:1]
	v_lshlrev_b32_e32 v2, 1, v2
	v_mov_b32_e32 v3, v193
	v_lshl_add_u64 v[14:15], v[0:1], 0, v[2:3]
	s_mov_b32 s9, 0x98000
	v_add_co_u32_e32 v4, vcc, s9, v14
	global_load_dwordx4 v[0:3], v[14:15], off
	s_nop 0
	v_addc_co_u32_e32 v5, vcc, 0, v15, vcc
	global_load_dwordx4 v[4:7], v[4:5], off
	s_nop 0
	global_load_dwordx4 v[8:11], v[12:13], off
	v_ashrrev_i32_e32 v49, 1, v70
	s_movk_i32 s9, 0xffe0
	v_bfe_u32 v134, v70, 5, 1
	v_bfi_b32 v18, s9, v49, v70
	v_mov_b64_e32 v[16:17], s[6:7]
	v_mad_i64_i32 v[16:17], s[6:7], v18, s93, v[16:17]
	v_lshlrev_b32_e32 v192, 4, v134
	v_lshl_add_u64 v[16:17], v[16:17], 0, v[192:193]
	global_load_dwordx4 v[100:103], v[16:17], off
	global_load_dwordx4 v[96:99], v[16:17], off offset:32
	global_load_dwordx4 v[108:111], v[16:17], off offset:64
	global_load_dwordx4 v[104:107], v[16:17], off offset:96
	v_and_b32_e32 v19, 0xfffff0, v62
	v_lshlrev_b32_e32 v20, 1, v62
	v_lshrrev_b32_e32 v21, 1, v62
	v_and_b32_e32 v23, 3, v62
	v_add_u32_e32 v25, 32, v62
	v_and_b32_e32 v18, 0x70, v70
	v_lshlrev_b32_e32 v26, 7, v64
	v_and_or_b32 v19, v20, 8, v19
	v_and_or_b32 v20, v21, 4, v23
	v_and_b32_e32 v21, 0xfffff0, v25
	v_lshlrev_b32_e32 v23, 1, v25
	v_bfe_u32 v22, v32, 5, 2
	v_bitop3_b32 v18, v48, v26, v18 bitop3:0xde
	v_lshrrev_b32_e32 v19, 1, v19
	v_and_or_b32 v21, v23, 8, v21
	v_add_u32_e32 v140, 16, v18
	v_or_b32_e32 v18, v19, v22
	v_lshrrev_b32_e32 v19, 1, v21
	v_and_b32_e32 v135, 31, v70
	v_and_b32_e32 v24, 48, v63
	v_lshlrev_b32_e32 v20, 6, v20
	v_lshlrev_b32_e32 v18, 9, v18
	v_or_b32_e32 v19, v19, v22
	v_lshl_add_u32 v65, v135, 7, 16
	v_bitop3_b32 v25, v192, v32, s46 bitop3:0x78
	v_or3_b32 v18, v18, v20, v24
	v_lshlrev_b32_e32 v19, 9, v19
	v_or3_b32 v19, v19, v20, v24
	v_add_u32_e32 v141, 16, v18
	v_add_u32_e32 v143, v65, v25
	v_add_u32_e32 v142, 16, v19
	s_waitcnt vmcnt(0)
	s_mov_b32 s6, 0x130000
	s_mov_b32 s7, 0x1c8000
	v_and_b32_e32 v71, 63, v70
	v_and_b32_e32 v124, 0xffffffe0, v49
	s_cmp_lg_u32 16, -1
	s_waitcnt vmcnt(6)
	ds_write_b128 v141, v[0:3]
	s_waitcnt vmcnt(5)
	ds_write_b128 v142, v[4:7]
	s_waitcnt vmcnt(4)
	ds_write_b128 v140, v[8:11] offset:32768
	s_waitcnt lgkmcnt(0)
	s_barrier
	ds_read_b128 v[0:3], v143 offset:32768
	ds_read_b128 v[4:7], v143 offset:36864
	v_and_b32_e32 v8, 0x70, v32
	s_waitcnt vmcnt(3) lgkmcnt(0)
	v_mfma_f32_32x32x16_bf16 v[32:47], v[4:7], v[100:103], 0
	v_add_co_u32_e32 v4, vcc, s6, v14
	s_cselect_b32 s9, 16, 0
	s_nop 0
	v_addc_co_u32_e32 v5, vcc, 0, v15, vcc
	v_add_co_u32_e32 v6, vcc, s7, v14
	v_mfma_f32_32x32x16_bf16 v[16:31], v[0:3], v[100:103], 0
	v_bitop3_b32 v0, v192, v8, 32 bitop3:0x36
	v_add_u32_e32 v144, v65, v0
	v_addc_co_u32_e32 v7, vcc, 0, v15, vcc
	ds_read_b128 v[0:3], v144 offset:32768
	global_load_dwordx4 v[50:53], v[4:5], off
	global_load_dwordx4 v[54:57], v[6:7], off
	v_add_co_u32_e32 v4, vcc, s6, v12
	s_waitcnt vmcnt(4) lgkmcnt(0)
	v_mfma_f32_32x32x16_bf16 v[16:31], v[0:3], v[96:99], v[16:31]
	v_addc_co_u32_e32 v5, vcc, 0, v13, vcc
	global_load_dwordx4 v[58:61], v[4:5], off
	v_lshlrev_b32_e32 v0, 3, v71
	v_and_b32_e32 v1, 0xc0, v63
	v_lshlrev_b32_e32 v2, 1, v70
	v_and_or_b32 v1, v0, 24, v1
	v_and_b32_e32 v2, 32, v2
	v_and_b32_e32 v0, 0x100, v0
	v_or3_b32 v49, v1, v2, v0
	v_bitop3_b32 v0, v192, v8, 64 bitop3:0x36
	v_add_u32_e32 v146, v65, v0
	ds_read_b128 v[0:3], v146 offset:32768
	v_and_b32_e32 v4, 0x3fffffc0, v70
	v_lshl_add_u32 v125, v4, 2, 16
	ds_read_b128 v[4:7], v144 offset:36864
	v_mad_i64_i32 v[66:67], s[6:7], v64, s93, 0
	v_mad_i64_i32 v[68:69], s[6:7], v62, s93, 0
	s_movk_i32 s6, 0x60
	s_waitcnt vmcnt(4) lgkmcnt(1)
	v_mfma_f32_32x32x16_bf16 v[16:31], v[0:3], v[108:111], v[16:31]
	v_bitop3_b32 v0, v192, v8, s6 bitop3:0x36
	v_add_u32_e32 v145, v65, v0
	ds_read_b128 v[0:3], v145 offset:32768
	ds_read_b128 v[62:65], v145 offset:36864
	v_add_u32_e32 v139, s9, v49
	v_readlane_b32 s10, v254, 4
	s_mov_b32 s36, s37
	s_waitcnt lgkmcnt(2)
	v_mfma_f32_32x32x16_bf16 v[32:47], v[4:7], v[96:99], v[32:47]
	ds_read_b128 v[4:7], v146 offset:36864
	s_waitcnt vmcnt(0)
	s_waitcnt vmcnt(2)
	ds_write_b128 v141, v[50:53] offset:16384
	s_waitcnt vmcnt(1)
	ds_write_b128 v142, v[54:57] offset:16384
	s_waitcnt vmcnt(0)
	ds_write_b128 v140, v[58:61] offset:40960
	s_waitcnt lgkmcnt(3)
; DEVI void partialSM(f32x16& p0, f32x16& p1, float& m_reg, float& mn, float& alpha, float scale) {
;   const float C = scale * 1.4426950408889634f;
;   float pmax = p0[0];
; #pragma unroll
;   for (int r = 1; r < 16; ++r) pmax = fmaxf(pmax, p0[r]);
; #pragma unroll
;   for (int r = 0; r < 16; ++r) pmax = fmaxf(pmax, p1[r]);
;   { auto rr = __builtin_amdgcn_permlane32_swap(__float_as_uint(pmax), __float_as_uint(pmax), false, false);
;     pmax = fmaxf(__uint_as_float(rr[0]), __uint_as_float(rr[1])); }
;   if (__builtin_expect(__all(pmax - m_reg <= ATT_THR / scale), 1)) { mn = m_reg; alpha = 1.f; }
;   else { mn = fmaxf(m_reg, pmax); alpha = __builtin_amdgcn_exp2f((m_reg - mn) * C); m_reg = mn; }
;   const float mnC = -mn * C;
; #pragma unroll
;   for (int r = 0; r < 16; ++r) p0[r] = fmaf(p0[r], C, mnC);
; #pragma unroll
;   for (int r = 0; r < 16; ++r) p1[r] = fmaf(p1[r], C, mnC);
; #pragma unroll
;   for (int r = 0; r < 16; ++r) p0[r] = __builtin_amdgcn_exp2f(p0[r]);
; template <int DQK, bool PIPE>
; DEVI void attn_body(const u16* __restrict__ Qb, int ldq, const u16* __restrict__ K0, int ldk0, const u16* __restrict__ K1, int ldk1,
;                     const u16* __restrict__ Vh, int ldv, u16* __restrict__ Ob, int ldo, int seq, float scale, char* lds) {
;     ...
;   float m_reg = -1e30f, l_reg = 0; f32x16 o[4];
; #pragma unroll
;   for (int d = 0; d < 4; ++d)
; #pragma unroll
;     for (int r = 0; r < 16; ++r) o[d][r] = 0.f;
	v_mfma_f32_32x32x16_bf16 v[32:47], v[4:7], v[108:111], v[32:47]
	s_mov_b32 s38, s37
	s_mov_b32 s39, s37
	s_mov_b32 s40, s37
	s_mov_b32 s41, s37
	s_mov_b32 s42, s37
	s_mov_b32 s43, s37
	s_mov_b32 s44, s37
	v_mfma_f32_32x32x16_bf16 v[16:31], v[0:3], v[104:107], v[16:31]
	s_mov_b32 s45, s37
	s_mov_b32 s46, s37
	s_mov_b32 s47, s37
	s_mov_b32 s48, s37
	s_mov_b32 s49, s37
	s_mov_b32 s50, s37
	s_mov_b32 s51, s37
	v_mfma_f32_32x32x16_bf16 v[32:47], v[62:65], v[104:107], v[32:47]
	s_nop 3
	v_max_f32_e32 v62, v17, v17
	v_max_f32_e32 v63, v16, v16
	v_max_f32_e32 v62, v63, v62
	v_max3_f32 v62, v62, v18, v19
	v_max3_f32 v62, v62, v20, v21
	v_max3_f32 v62, v62, v22, v23
	v_max3_f32 v62, v62, v24, v25
	v_max3_f32 v62, v62, v26, v27
	v_max3_f32 v62, v62, v28, v29
	v_max3_f32 v62, v62, v30, v31
	v_max3_f32 v62, v62, v32, v33
	v_max3_f32 v62, v62, v34, v35
	v_max3_f32 v62, v62, v36, v37
	v_max3_f32 v62, v62, v38, v39
	v_max3_f32 v62, v62, v40, v41
	v_max3_f32 v62, v62, v42, v43
	v_max3_f32 v62, v62, v44, v45
	v_max3_f32 v62, v62, v46, v47
	v_mov_b32_e32 v63, v62
	s_nop 1
	v_permlane32_swap_b32_e32 v62, v63
	v_max_f32_e32 v63, v63, v63
	v_max_f32_e32 v62, v62, v62
	v_max_f32_e32 v62, v62, v63
	v_add_f32_e32 v63, 0x7149f2ca, v62
	v_cmp_ge_f32_e32 vcc, s64, v63
	s_cmp_eq_u64 vcc, exec
	v_max_f32_e32 v50, 0xf149f2ca, v62
	s_cselect_b64 vcc, -1, 0
	v_cndmask_b32_e32 v148, v50, v215, vcc
	v_sub_f32_e32 v51, 0xf149f2ca, v50
	v_mul_f32_e32 v50, 0xbe38aa3b, v148
	v_fmamk_f32 v16, v16, 0x3e38aa3b, v50
	v_exp_f32_e32 v157, v16
	v_fmamk_f32 v16, v17, 0x3e38aa3b, v50
	v_exp_f32_e32 v159, v16
	v_fmamk_f32 v16, v18, 0x3e38aa3b, v50
	v_exp_f32_e32 v161, v16
	v_fmamk_f32 v16, v19, 0x3e38aa3b, v50
	v_exp_f32_e32 v163, v16
	v_fmamk_f32 v16, v20, 0x3e38aa3b, v50
	v_exp_f32_e32 v165, v16
	v_fmamk_f32 v16, v21, 0x3e38aa3b, v50
	v_exp_f32_e32 v167, v16
	v_fmamk_f32 v16, v22, 0x3e38aa3b, v50
	v_exp_f32_e32 v168, v16
	v_fmamk_f32 v16, v23, 0x3e38aa3b, v50
	v_exp_f32_e32 v170, v16
	v_fmamk_f32 v16, v24, 0x3e38aa3b, v50
	v_exp_f32_e32 v155, v16
	v_fmamk_f32 v16, v25, 0x3e38aa3b, v50
	v_exp_f32_e32 v156, v16
	v_fmamk_f32 v16, v26, 0x3e38aa3b, v50
	v_exp_f32_e32 v158, v16
	v_fmamk_f32 v16, v27, 0x3e38aa3b, v50
	v_mul_f32_e32 v51, 0x3e38aa3b, v51
	v_exp_f32_e32 v160, v16
	v_fmamk_f32 v16, v28, 0x3e38aa3b, v50
	s_addk_i32 s9, 0x4000
	v_exp_f32_e32 v51, v51
	v_exp_f32_e32 v162, v16
	v_fmamk_f32 v16, v29, 0x3e38aa3b, v50
	v_add_u32_e32 v138, s9, v49
	s_lshl_b32 s9, s17, 5
	v_exp_f32_e32 v164, v16
	v_fmamk_f32 v16, v30, 0x3e38aa3b, v50
	s_and_b32 s9, s9, 0x400
	v_exp_f32_e32 v166, v16
	s_or_b32 s9, s9, s10
	v_mad_i64_i32 v[16:17], s[10:11], s8, v251, v[68:69]
	v_and_b32_e32 v18, 15, v70
	v_mov_b64_e32 v[0:1], s[36:37]
	v_lshl_or_b32 v16, v18, 4, v16
	v_mov_b64_e32 v[2:3], s[38:39]
	v_mov_b64_e32 v[4:5], s[40:41]
	v_mov_b64_e32 v[6:7], s[42:43]
	v_mov_b64_e32 v[8:9], s[44:45]
	v_mov_b64_e32 v[10:11], s[46:47]
	v_mov_b64_e32 v[12:13], s[48:49]
	v_mov_b64_e32 v[14:15], s[50:51]
	v_pk_fma_f32 v[112:113], v[46:47], s[20:21], v[50:51] op_sel_hi:[1,0,0]
	v_pk_fma_f32 v[118:119], v[44:45], s[20:21], v[50:51] op_sel_hi:[1,0,0]
	v_pk_fma_f32 v[122:123], v[42:43], s[20:21], v[50:51] op_sel_hi:[1,0,0]
	v_pk_fma_f32 v[114:115], v[40:41], s[20:21], v[50:51] op_sel_hi:[1,0,0]
	v_pk_fma_f32 v[116:117], v[38:39], s[20:21], v[50:51] op_sel_hi:[1,0,0]
	v_pk_fma_f32 v[120:121], v[36:37], s[20:21], v[50:51] op_sel_hi:[1,0,0]
	v_pk_fma_f32 v[130:131], v[34:35], s[20:21], v[50:51] op_sel_hi:[1,0,0]
	v_pk_fma_f32 v[132:133], v[32:33], s[20:21], v[50:51] op_sel_hi:[1,0,0]
	v_fmac_f32_e32 v50, 0x3e38aa3b, v31
	s_and_b32 s36, s9, 0x700
	v_lshl_add_u64 v[126:127], s[90:91], 0, v[16:17]
	v_mad_i64_i32 v[16:17], s[8:9], s8, v251, v[66:67]
	v_exp_f32_e32 v169, v50
	v_readlane_b32 s8, v253, 63
	v_or_b32_e32 v16, v16, v48
	v_readlane_b32 s9, v254, 0
	v_readlane_b32 s44, v254, 12
	v_cndmask_b32_e64 v147, v51, 1.0, vcc
	v_lshl_add_u64 v[128:129], s[8:9], 0, v[16:17]
	v_mov_b64_e32 v[62:63], v[14:15]
	v_mov_b64_e32 v[46:47], v[14:15]
	v_mov_b64_e32 v[30:31], v[14:15]
	s_mov_b32 s15, -1
	s_movk_i32 s38, 0x80
	s_movk_i32 s46, 0x70
	v_readlane_b32 s45, v254, 13
	v_readlane_b32 s47, v252, 42
	v_cmp_gt_u32_e64 s[6:7], 32, v71
	v_lshl_add_u32 v136, v135, 2, v125
	v_mov_b32_e32 v137, 0
	v_mov_b64_e32 v[60:61], v[12:13]
	v_mov_b64_e32 v[58:59], v[10:11]
	v_mov_b64_e32 v[56:57], v[8:9]
	v_mov_b64_e32 v[54:55], v[6:7]
	v_mov_b64_e32 v[52:53], v[4:5]
	v_mov_b64_e32 v[50:51], v[2:3]
	v_mov_b64_e32 v[48:49], v[0:1]
	v_mov_b64_e32 v[44:45], v[12:13]
	v_mov_b64_e32 v[42:43], v[10:11]
	v_mov_b64_e32 v[40:41], v[8:9]
	v_mov_b64_e32 v[38:39], v[6:7]
	v_mov_b64_e32 v[36:37], v[4:5]
	v_mov_b64_e32 v[34:35], v[2:3]
	v_mov_b64_e32 v[32:33], v[0:1]
	v_mov_b64_e32 v[28:29], v[12:13]
	v_mov_b64_e32 v[26:27], v[10:11]
	v_mov_b64_e32 v[24:25], v[8:9]
	v_mov_b64_e32 v[22:23], v[6:7]
	v_mov_b64_e32 v[20:21], v[4:5]
	v_mov_b64_e32 v[18:19], v[2:3]
	v_mov_b64_e32 v[16:17], v[0:1]
	s_waitcnt lgkmcnt(0)
	s_barrier
	v_readfirstlane_b32 s8, v208
	s_nop 3
	s_cmpk_lt_u32 s8, 0x100
	s_cbranch_scc1 .Ldiff_prio_skip
	s_setprio 1
; template <int D0> DEVI void pv_one(f32x16& od, int vb, bf16x8 pa0, bf16x8 pa1, bf16x8 pa2, bf16x8 pa3) {
;   const s16x4 l0 = tr_read<v_rd_off(D0, 0, 0)>(vb), h0 = tr_read<v_rd_off(D0, 0, 1)>(vb), l1 = tr_read<v_rd_off(D0, 1, 0)>(vb), h1 = tr_read<v_rd_off(D0, 1, 1)>(vb);
;   const s16x4 l2 = tr_read<v_rd_off(D0, 2, 0)>(vb), h2 = tr_read<v_rd_off(D0, 2, 1)>(vb), l3 = tr_read<v_rd_off(D0, 3, 0)>(vb), h3 = tr_read<v_rd_off(D0, 3, 1)>(vb);
;   asm volatile("s_waitcnt lgkmcnt(0)" ::: "memory"); SBAR();
;     ...
;   od = __builtin_amdgcn_mfma_f32_32x32x16_bf16(pa0, PK(l0, h0), od, 0, 0, 0);
;   od = __builtin_amdgcn_mfma_f32_32x32x16_bf16(pa1, PK(l1, h1), od, 0, 0, 0);
;   od = __builtin_amdgcn_mfma_f32_32x32x16_bf16(pa2, PK(l2, h2), od, 0, 0, 0);
;   od = __builtin_amdgcn_mfma_f32_32x32x16_bf16(pa3, PK(l3, h3), od, 0, 0, 0);
;     ...
; }
; DEVI void pv_d0(f32x16* o, int vb, bf16x8 pa0, bf16x8 pa1, bf16x8 pa2, bf16x8 pa3) {
;   pv_one<0>(o[0], vb, pa0, pa1, pa2, pa3); pv_one<1>(o[1], vb, pa0, pa1, pa2, pa3); pv_one<2>(o[2], vb, pa0, pa1, pa2, pa3); pv_one<3>(o[3], vb, pa0, pa1, pa2, pa3);
; }
; DEVI void partialSM(f32x16& p0, f32x16& p1, float& m_reg, float& mn, float& alpha, float scale) {
;   const float C = scale * 1.4426950408889634f;
;   float pmax = p0[0];
; #pragma unroll
;   for (int r = 1; r < 16; ++r) pmax = fmaxf(pmax, p0[r]);
; #pragma unroll
;   for (int r = 0; r < 16; ++r) pmax = fmaxf(pmax, p1[r]);
;   { auto rr = __builtin_amdgcn_permlane32_swap(__float_as_uint(pmax), __float_as_uint(pmax), false, false);
;     pmax = fmaxf(__uint_as_float(rr[0]), __uint_as_float(rr[1])); }
;   if (__builtin_expect(__all(pmax - m_reg <= ATT_THR / scale), 1)) { mn = m_reg; alpha = 1.f; }
;   else { mn = fmaxf(m_reg, pmax); alpha = __builtin_amdgcn_exp2f((m_reg - mn) * C); m_reg = mn; }
;   const float mnC = -mn * C;
; #pragma unroll
;   for (int r = 0; r < 16; ++r) p0[r] = fmaf(p0[r], C, mnC);
; #pragma unroll
;   for (int r = 0; r < 16; ++r) p1[r] = fmaf(p1[r], C, mnC);
; #pragma unroll
;   for (int r = 0; r < 16; ++r) p0[r] = __builtin_amdgcn_exp2f(p0[r]);
; }
; DEVI void finishSM(f32x16& p0, f32x16& p1, float alpha, float& l_reg, bf16x8& pa0, bf16x8& pa1, bf16x8& pa2, bf16x8& pa3) {
; #pragma unroll
;   for (int r = 0; r < 16; ++r) p1[r] = __builtin_amdgcn_exp2f(p1[r]);
;   float ps = 0;
; #pragma unroll
;   for (int r = 0; r < 16; ++r) ps += p0[r];
; #pragma unroll
.Ldiff_prio_skip:
.LBB0_469:
	ds_read_b128 v[64:67], v143 offset:40960
	ds_read_b128 v[68:71], v143 offset:45056
	v_add_f32_e32 v149, 0, v157
	v_add_f32_e32 v149, v159, v149
	v_add_f32_e32 v149, v161, v149
	s_waitcnt lgkmcnt(1)
	v_mfma_f32_32x32x16_bf16 v[80:95], v[64:67], v[100:103], 0
	v_add_f32_e32 v149, v163, v149
	v_add_f32_e32 v149, v165, v149
	ds_read_b128 v[150:153], v144 offset:40960
	ds_read_b128 v[172:175], v144 offset:45056
	v_add_f32_e32 v149, v167, v149
	v_add_f32_e32 v149, v168, v149
	v_add_f32_e32 v149, v170, v149
	v_add_f32_e32 v149, v155, v149
	s_waitcnt lgkmcnt(2)
	v_mfma_f32_32x32x16_bf16 v[64:79], v[68:71], v[100:103], 0
	v_add_f32_e32 v149, v156, v149
	v_add_f32_e32 v149, v158, v149
	v_add_f32_e32 v149, v160, v149
	v_exp_f32_e32 v132, v132
	v_add_f32_e32 v149, v162, v149
	v_exp_f32_e32 v133, v133
	v_add_f32_e32 v149, v164, v149
	s_waitcnt lgkmcnt(1)
	v_mfma_f32_32x32x16_bf16 v[80:95], v[150:153], v[96:99], v[80:95]
	v_exp_f32_e32 v130, v130
	v_add_f32_e32 v149, v166, v149
	v_exp_f32_e32 v131, v131
	v_add_f32_e32 v149, v169, v149
	v_exp_f32_e32 v120, v120
	v_add_f32_e32 v149, v132, v149
	v_exp_f32_e32 v121, v121
	s_waitcnt lgkmcnt(0)
	v_mfma_f32_32x32x16_bf16 v[64:79], v[172:175], v[96:99], v[64:79]
	ds_read_b128 v[150:153], v146 offset:40960
	ds_read_b128 v[172:175], v146 offset:45056
	v_add_f32_e32 v149, v133, v149
	v_exp_f32_e32 v116, v116
	v_add_f32_e32 v149, v130, v149
	v_exp_f32_e32 v117, v117
	v_add_f32_e32 v149, v131, v149
	v_exp_f32_e32 v114, v114
	s_waitcnt lgkmcnt(1)
	v_mfma_f32_32x32x16_bf16 v[80:95], v[150:153], v[108:111], v[80:95]
	v_add_f32_e32 v149, v120, v149
	v_exp_f32_e32 v115, v115
	v_add_f32_e32 v149, v121, v149
	v_exp_f32_e32 v122, v122
	v_add_f32_e32 v149, v116, v149
	v_exp_f32_e32 v123, v123
	v_add_f32_e32 v149, v117, v149
	s_waitcnt lgkmcnt(0)
	v_mfma_f32_32x32x16_bf16 v[64:79], v[172:175], v[108:111], v[64:79]
	ds_read_b128 v[150:153], v145 offset:40960
	ds_read_b128 v[172:175], v145 offset:45056
	v_exp_f32_e32 v118, v118
	v_add_f32_e32 v149, v114, v149
	v_exp_f32_e32 v119, v119
	v_add_f32_e32 v149, v115, v149
	v_exp_f32_e32 v112, v112
	v_add_f32_e32 v149, v122, v149
	s_waitcnt lgkmcnt(1)
	v_mfma_f32_32x32x16_bf16 v[80:95], v[150:153], v[104:107], v[80:95]
	v_exp_f32_e32 v113, v113
	v_add_f32_e32 v149, v123, v149
	v_add_f32_e32 v149, v118, v149
	v_add_f32_e32 v149, v119, v149
	v_add_f32_e32 v149, v112, v149
	v_add_f32_e32 v149, v113, v149
	v_mov_b32_e32 v150, v149
	s_waitcnt lgkmcnt(0)
	v_mfma_f32_32x32x16_bf16 v[64:79], v[172:175], v[104:107], v[64:79]
	v_cvt_pk_bf16_f32 v152, v155, v156
	v_cvt_pk_bf16_f32 v154, v162, v164
	v_permlane32_swap_b32_e32 v149, v150
	v_cvt_pk_bf16_f32 v172, v157, v159
	v_cvt_pk_bf16_f32 v173, v161, v163
	v_cvt_pk_bf16_f32 v174, v165, v167
	v_cvt_pk_bf16_f32 v175, v168, v170
	v_cvt_pk_bf16_f32 v153, v158, v160
	v_cvt_pk_bf16_f32 v155, v166, v169
	v_permlane32_swap_b32_e32 v152, v154
	v_cvt_pk_bf16_f32 v156, v132, v133
	v_cvt_pk_bf16_f32 v157, v130, v131
	v_cvt_pk_bf16_f32 v158, v120, v121
	v_cvt_pk_bf16_f32 v159, v116, v117
	v_cvt_pk_bf16_f32 v160, v114, v115
	v_cvt_pk_bf16_f32 v161, v122, v123
	v_cvt_pk_bf16_f32 v162, v118, v119
	v_cvt_pk_bf16_f32 v163, v112, v113
	v_permlane32_swap_b32_e32 v172, v174
	v_permlane32_swap_b32_e32 v173, v175
	v_permlane32_swap_b32_e32 v153, v155
	v_permlane32_swap_b32_e32 v156, v158
	v_permlane32_swap_b32_e32 v157, v159
	v_permlane32_swap_b32_e32 v160, v162
	v_permlane32_swap_b32_e32 v161, v163
	v_lshl_add_u64 v[130:131], v[126:127], 0, s[36:37]
	s_mov_b32 s8, 0x814f000
	v_add_co_u32_e32 v112, vcc, s8, v130
	s_mov_b32 s8, 0x81e7000
	s_nop 0
	v_addc_co_u32_e32 v113, vcc, 0, v131, vcc
	v_add_co_u32_e32 v116, vcc, s8, v130
	v_lshl_add_u64 v[132:133], v[128:129], 0, s[36:37]
	s_nop 0
	v_addc_co_u32_e32 v117, vcc, 0, v131, vcc
	s_mov_b32 s8, 0x814e000
	v_add_co_u32_e32 v120, vcc, s8, v132
	global_load_dwordx4 v[112:115], v[112:113], off
	s_nop 0
	global_load_dwordx4 v[116:119], v[116:117], off
	v_addc_co_u32_e32 v121, vcc, 0, v133, vcc
	global_load_dwordx4 v[120:123], v[120:121], off offset:2048
	ds_read_b64_tr_b16 v[164:165], v139 offset:0
	ds_read_b64_tr_b16 v[166:167], v139 offset:0x800
	ds_read_b64_tr_b16 v[168:169], v139 offset:0x1000
	ds_read_b64_tr_b16 v[170:171], v139 offset:0x1800
	ds_read_b64_tr_b16 v[176:177], v139 offset:0x2000
	ds_read_b64_tr_b16 v[178:179], v139 offset:0x2800
	ds_read_b64_tr_b16 v[180:181], v139 offset:0x3000
	ds_read_b64_tr_b16 v[182:183], v139 offset:0x3800
	s_waitcnt lgkmcnt(0)
	s_nop 0
	v_mfma_f32_32x32x16_bf16 v[0:15], v[172:175], v[164:167], v[0:15]
	ds_read_b64_tr_b16 v[164:165], v139 offset:0x200
	ds_read_b64_tr_b16 v[166:167], v139 offset:0xa00
	v_mfma_f32_32x32x16_bf16 v[0:15], v[152:155], v[168:171], v[0:15]
	ds_read_b64_tr_b16 v[168:169], v139 offset:0x1200
	ds_read_b64_tr_b16 v[170:171], v139 offset:0x1a00
	v_mfma_f32_32x32x16_bf16 v[0:15], v[156:159], v[176:179], v[0:15]
	ds_read_b64_tr_b16 v[176:177], v139 offset:0x2200
	ds_read_b64_tr_b16 v[178:179], v139 offset:0x2a00
	v_mfma_f32_32x32x16_bf16 v[0:15], v[160:163], v[180:183], v[0:15]
	ds_read_b64_tr_b16 v[180:181], v139 offset:0x3200
	ds_read_b64_tr_b16 v[182:183], v139 offset:0x3a00
	s_waitcnt lgkmcnt(0)
	v_mfma_f32_32x32x16_bf16 v[48:63], v[172:175], v[164:167], v[48:63]
	ds_read_b64_tr_b16 v[164:165], v139 offset:0x400
	ds_read_b64_tr_b16 v[166:167], v139 offset:0xc00
	v_mfma_f32_32x32x16_bf16 v[48:63], v[152:155], v[168:171], v[48:63]
	ds_read_b64_tr_b16 v[168:169], v139 offset:0x1400
	ds_read_b64_tr_b16 v[170:171], v139 offset:0x1c00
	v_mfma_f32_32x32x16_bf16 v[48:63], v[156:159], v[176:179], v[48:63]
	ds_read_b64_tr_b16 v[176:177], v139 offset:0x2400
	ds_read_b64_tr_b16 v[178:179], v139 offset:0x2c00
	v_mfma_f32_32x32x16_bf16 v[48:63], v[160:163], v[180:183], v[48:63]
	ds_read_b64_tr_b16 v[180:181], v139 offset:0x3400
	ds_read_b64_tr_b16 v[182:183], v139 offset:0x3c00
	s_waitcnt lgkmcnt(0)
	v_mfma_f32_32x32x16_bf16 v[32:47], v[172:175], v[164:167], v[32:47]
	ds_read_b64_tr_b16 v[164:165], v139 offset:0x600
	ds_read_b64_tr_b16 v[166:167], v139 offset:0xe00
	v_mfma_f32_32x32x16_bf16 v[32:47], v[152:155], v[168:171], v[32:47]
	ds_read_b64_tr_b16 v[168:169], v139 offset:0x1600
	ds_read_b64_tr_b16 v[170:171], v139 offset:0x1e00
	v_mfma_f32_32x32x16_bf16 v[32:47], v[156:159], v[176:179], v[32:47]
	ds_read_b64_tr_b16 v[176:177], v139 offset:0x2600
	ds_read_b64_tr_b16 v[178:179], v139 offset:0x2e00
	v_mfma_f32_32x32x16_bf16 v[32:47], v[160:163], v[180:183], v[32:47]
	ds_read_b64_tr_b16 v[180:181], v139 offset:0x3600
	ds_read_b64_tr_b16 v[182:183], v139 offset:0x3e00
	s_waitcnt lgkmcnt(0)
	v_mfma_f32_32x32x16_bf16 v[16:31], v[172:175], v[164:167], v[16:31]
	v_max_f32_e32 v151, v81, v81
	s_barrier
; DEVI void partialSM(f32x16& p0, f32x16& p1, float& m_reg, float& mn, float& alpha, float scale) {
;   const float C = scale * 1.4426950408889634f;
;   float pmax = p0[0];
; #pragma unroll
;   for (int r = 1; r < 16; ++r) pmax = fmaxf(pmax, p0[r]);
; #pragma unroll
;   for (int r = 0; r < 16; ++r) pmax = fmaxf(pmax, p1[r]);
;   { auto rr = __builtin_amdgcn_permlane32_swap(__float_as_uint(pmax), __float_as_uint(pmax), false, false);
;     pmax = fmaxf(__uint_as_float(rr[0]), __uint_as_float(rr[1])); }
;   if (__builtin_expect(__all(pmax - m_reg <= ATT_THR / scale), 1)) { mn = m_reg; alpha = 1.f; }
;   else { mn = fmaxf(m_reg, pmax); alpha = __builtin_amdgcn_exp2f((m_reg - mn) * C); m_reg = mn; }
	s_waitcnt vmcnt(0)
	s_waitcnt vmcnt(2)
	ds_write_b128 v141, v[112:115]
	s_waitcnt vmcnt(1)
	ds_write_b128 v142, v[116:119]
	s_waitcnt vmcnt(0)
	ds_write_b128 v140, v[120:123] offset:32768
	v_mfma_f32_32x32x16_bf16 v[16:31], v[152:155], v[168:171], v[16:31]
	v_max_f32_e32 v152, v80, v80
	v_max_f32_e32 v151, v152, v151
	v_max3_f32 v151, v151, v82, v83
	v_max3_f32 v151, v151, v84, v85
	v_max3_f32 v151, v151, v86, v87
	v_max3_f32 v151, v151, v88, v89
	v_max3_f32 v151, v151, v90, v91
	v_max3_f32 v151, v151, v92, v93
	v_max3_f32 v151, v151, v94, v95
	v_max3_f32 v151, v151, v64, v65
	v_max3_f32 v151, v151, v66, v67
	v_max3_f32 v151, v151, v68, v69
	v_max3_f32 v151, v151, v70, v71
	v_max3_f32 v151, v151, v72, v73
	v_max3_f32 v151, v151, v74, v75
	v_max3_f32 v151, v151, v76, v77
	v_mfma_f32_32x32x16_bf16 v[16:31], v[156:159], v[176:179], v[16:31]
	v_max3_f32 v151, v151, v78, v79
	v_mov_b32_e32 v152, v151
	s_nop 1
	v_permlane32_swap_b32_e32 v151, v152
	v_max_f32_e32 v152, v152, v152
	v_max_f32_e32 v151, v151, v151
	v_max_f32_e32 v151, v151, v152
	v_sub_f32_e32 v152, v151, v148
	v_cmp_ge_f32_e32 vcc, s64, v152
	v_max_f32_e32 v152, v148, v148
	v_max_f32_e32 v151, v152, v151
	v_mfma_f32_32x32x16_bf16 v[16:31], v[160:163], v[180:183], v[16:31]
	v_sub_f32_e32 v152, v148, v151
	v_mul_f32_e32 v152, 0x3e38aa3b, v152
	v_exp_f32_e32 v152, v152
	s_cmp_eq_u64 vcc, exec
	s_cselect_b64 s[8:9], -1, 0
	v_cndmask_b32_e64 v152, v152, 1.0, s[8:9]
	v_cmp_gt_f32_e32 vcc, 1.0, v152
	s_cbranch_vccz .LBB0_473
	s_and_saveexec_b64 s[10:11], s[6:7]
	ds_write_b32 v136, v152 offset:49280
	s_or_b64 exec, exec, s[10:11]
	s_waitcnt lgkmcnt(0)
	v_add_u32_e32 v153, v125, v192
	ds_read_b128 v[112:115], v153 offset:49376
	ds_read_b128 v[116:119], v153 offset:49344
	ds_read_b128 v[120:123], v153 offset:49312
	ds_read_b128 v[154:157], v153 offset:49280
	s_waitcnt lgkmcnt(3)
	v_pk_mul_f32 v[12:13], v[12:13], v[112:113]
	s_waitcnt lgkmcnt(2)
	v_pk_mul_f32 v[8:9], v[8:9], v[116:117]
	s_waitcnt lgkmcnt(1)
	v_pk_mul_f32 v[4:5], v[4:5], v[120:121]
	v_pk_mul_f32 v[14:15], v[14:15], v[114:115]
	v_pk_mul_f32 v[10:11], v[10:11], v[118:119]
	v_pk_mul_f32 v[6:7], v[6:7], v[122:123]
	s_waitcnt lgkmcnt(0)
	v_pk_mul_f32 v[2:3], v[2:3], v[156:157]
	v_pk_mul_f32 v[0:1], v[0:1], v[154:155]
	v_pk_mul_f32 v[60:61], v[60:61], v[112:113]
	v_pk_mul_f32 v[56:57], v[56:57], v[116:117]
	v_pk_mul_f32 v[52:53], v[52:53], v[120:121]
	v_pk_mul_f32 v[62:63], v[62:63], v[114:115]
	v_pk_mul_f32 v[58:59], v[58:59], v[118:119]
	v_pk_mul_f32 v[54:55], v[54:55], v[122:123]
	v_pk_mul_f32 v[50:51], v[50:51], v[156:157]
	v_pk_mul_f32 v[48:49], v[48:49], v[154:155]
	v_pk_mul_f32 v[44:45], v[44:45], v[112:113]
	v_pk_mul_f32 v[40:41], v[40:41], v[116:117]
	v_pk_mul_f32 v[36:37], v[36:37], v[120:121]
	v_pk_mul_f32 v[46:47], v[46:47], v[114:115]
	v_pk_mul_f32 v[42:43], v[42:43], v[118:119]
	v_pk_mul_f32 v[38:39], v[38:39], v[122:123]
	v_pk_mul_f32 v[34:35], v[34:35], v[156:157]
	v_pk_mul_f32 v[32:33], v[32:33], v[154:155]
	v_pk_mul_f32 v[28:29], v[28:29], v[112:113]
	v_pk_mul_f32 v[24:25], v[24:25], v[116:117]
	v_pk_mul_f32 v[20:21], v[20:21], v[120:121]
	v_pk_mul_f32 v[30:31], v[30:31], v[114:115]
	v_pk_mul_f32 v[26:27], v[26:27], v[118:119]
	v_pk_mul_f32 v[22:23], v[22:23], v[122:123]
	v_pk_mul_f32 v[18:19], v[18:19], v[156:157]
	v_pk_mul_f32 v[16:17], v[16:17], v[154:155]

; #define SBAR() __builtin_amdgcn_sched_barrier(0)
; DEVI void finishSM(f32x16& p0, f32x16& p1, float alpha, float& l_reg, bf16x8& pa0, bf16x8& pa1, bf16x8& pa2, bf16x8& pa3) {
; #pragma unroll
;   for (int r = 0; r < 16; ++r) p1[r] = __builtin_amdgcn_exp2f(p1[r]);
;   float ps = 0;
; #pragma unroll
;   for (int r = 0; r < 16; ++r) ps += p0[r];
; #pragma unroll
;   for (int r = 0; r < 16; ++r) ps += p1[r];
;   { auto rr = __builtin_amdgcn_permlane32_swap(__float_as_uint(ps), __float_as_uint(ps), false, false);
;     ps = __uint_as_float(rr[0]) + __uint_as_float(rr[1]); }
;   l_reg = l_reg * alpha + ps;
;   PK4(p0, 0, pa0); PK4(p0, 8, pa1); PK4(p1, 0, pa2); PK4(p1, 8, pa3);
; }
; template <int DQK, bool PIPE>
; DEVI void attn_body(const u16* __restrict__ Qb, int ldq, const u16* __restrict__ K0, int ldk0, const u16* __restrict__ K1, int ldk1,
;                     const u16* __restrict__ Vh, int ldv, u16* __restrict__ Ob, int ldo, int seq, float scale, char* lds) {
;     ...
;     SBAR(); QKT(pB0, pB1, K_lds + SHM_K);
;     finishSM(pA0, pA1, alA, l_reg, pa0, pa1, pa2, pa3); SBAR();
;     pv_d0(o, vb0, pa0, pa1, pa2, pa3); partialSM(pB0, pB1, m_reg, mnB, alB, scale);
.LBB0_479:
	s_setprio 0
	ds_read_b128 v[64:67], v143 offset:40960
	ds_read_b128 v[68:71], v143 offset:45056
	v_exp_f32_e32 v116, v116
	v_exp_f32_e32 v117, v117
	v_exp_f32_e32 v114, v114
	s_waitcnt lgkmcnt(1)
	v_mfma_f32_32x32x16_bf16 v[80:95], v[64:67], v[100:103], 0
	v_exp_f32_e32 v115, v115
	v_exp_f32_e32 v118, v118
	v_exp_f32_e32 v119, v119
	v_exp_f32_e32 v113, v113
	s_waitcnt lgkmcnt(0)
	v_mfma_f32_32x32x16_bf16 v[64:79], v[68:71], v[100:103], 0
	ds_read_b128 v[100:103], v144 offset:40960
	ds_read_b128 v[126:129], v144 offset:45056
	s_waitcnt lgkmcnt(1)
	v_mfma_f32_32x32x16_bf16 v[80:95], v[100:103], v[96:99], v[80:95]
	s_waitcnt lgkmcnt(0)
	v_mfma_f32_32x32x16_bf16 v[64:79], v[126:129], v[96:99], v[64:79]
	ds_read_b128 v[96:99], v146 offset:40960
	ds_read_b128 v[100:103], v146 offset:45056
	s_waitcnt lgkmcnt(1)
	v_mfma_f32_32x32x16_bf16 v[80:95], v[96:99], v[108:111], v[80:95]
	s_waitcnt lgkmcnt(0)
	v_mfma_f32_32x32x16_bf16 v[64:79], v[100:103], v[108:111], v[64:79]
	ds_read_b128 v[96:99], v145 offset:40960
	ds_read_b128 v[100:103], v145 offset:45056
	v_exp_f32_e32 v108, v130
	v_exp_f32_e32 v109, v131
	v_exp_f32_e32 v110, v120
	v_exp_f32_e32 v111, v121
	v_exp_f32_e32 v120, v122
	v_exp_f32_e32 v121, v123
	s_waitcnt lgkmcnt(1)
	v_mfma_f32_32x32x16_bf16 v[80:95], v[96:99], v[104:107], v[80:95]
	v_add_f32_e32 v96, 0, v157
	v_add_f32_e32 v96, v159, v96
	v_add_f32_e32 v96, v161, v96
	v_add_f32_e32 v96, v163, v96
	v_add_f32_e32 v96, v165, v96
	v_add_f32_e32 v96, v167, v96
	v_add_f32_e32 v96, v168, v96
	v_add_f32_e32 v96, v170, v96
	v_add_f32_e32 v96, v155, v96
	v_add_f32_e32 v96, v156, v96
	v_add_f32_e32 v96, v158, v96
	v_add_f32_e32 v96, v160, v96
	s_waitcnt lgkmcnt(0)
	v_mfma_f32_32x32x16_bf16 v[64:79], v[100:103], v[104:107], v[64:79]
	v_exp_f32_e32 v106, v132
	v_add_f32_e32 v96, v162, v96
	v_exp_f32_e32 v107, v133
	v_add_f32_e32 v96, v164, v96
	v_add_f32_e32 v96, v166, v96
	v_add_f32_e32 v96, v169, v96
	v_add_f32_e32 v96, v106, v96
	v_add_f32_e32 v96, v107, v96
	v_add_f32_e32 v96, v108, v96
	v_add_f32_e32 v96, v109, v96
	v_add_f32_e32 v96, v110, v96
	v_add_f32_e32 v96, v111, v96
	v_add_f32_e32 v96, v116, v96
	v_add_f32_e32 v96, v117, v96
	v_add_f32_e32 v96, v114, v96
	v_add_f32_e32 v96, v115, v96
	v_exp_f32_e32 v122, v112
	v_add_f32_e32 v96, v120, v96
	v_add_f32_e32 v96, v121, v96
	v_add_f32_e32 v96, v118, v96
	v_add_f32_e32 v96, v119, v96
	v_add_f32_e32 v96, v122, v96
	v_add_f32_e32 v96, v113, v96
	v_mov_b32_e32 v97, v96
	v_cvt_pk_bf16_f32 v98, v157, v159
	v_cvt_pk_bf16_f32 v99, v161, v163
	v_cvt_pk_bf16_f32 v100, v165, v167
	v_cvt_pk_bf16_f32 v101, v168, v170
	v_permlane32_swap_b32_e32 v96, v97
	v_permlane32_swap_b32_e32 v98, v100
	v_permlane32_swap_b32_e32 v99, v101
	v_cvt_pk_bf16_f32 v102, v155, v156
	v_cvt_pk_bf16_f32 v103, v158, v160
	v_cvt_pk_bf16_f32 v104, v162, v164
	v_cvt_pk_bf16_f32 v105, v166, v169
	v_cvt_pk_bf16_f32 v106, v106, v107
	v_cvt_pk_bf16_f32 v107, v108, v109
	v_cvt_pk_bf16_f32 v108, v110, v111
	v_cvt_pk_bf16_f32 v109, v116, v117
	v_cvt_pk_bf16_f32 v110, v114, v115
	v_cvt_pk_bf16_f32 v111, v120, v121
	v_cvt_pk_bf16_f32 v112, v118, v119
	v_cvt_pk_bf16_f32 v113, v122, v113
	v_permlane32_swap_b32_e32 v102, v104
	v_permlane32_swap_b32_e32 v103, v105
	v_permlane32_swap_b32_e32 v106, v108
	v_permlane32_swap_b32_e32 v107, v109
	v_permlane32_swap_b32_e32 v110, v112
	v_permlane32_swap_b32_e32 v111, v113
	ds_read_b64_tr_b16 v[114:115], v139 offset:0
	ds_read_b64_tr_b16 v[116:117], v139 offset:0x800
	ds_read_b64_tr_b16 v[118:119], v139 offset:0x1000
	ds_read_b64_tr_b16 v[120:121], v139 offset:0x1800
	ds_read_b64_tr_b16 v[126:127], v139 offset:0x2000
	ds_read_b64_tr_b16 v[128:129], v139 offset:0x2800
	ds_read_b64_tr_b16 v[130:131], v139 offset:0x3000
	ds_read_b64_tr_b16 v[132:133], v139 offset:0x3800
	s_waitcnt lgkmcnt(0)
	s_nop 0
	v_mfma_f32_32x32x16_bf16 v[0:15], v[98:101], v[114:117], v[0:15]
	ds_read_b64_tr_b16 v[114:115], v139 offset:0x200
	ds_read_b64_tr_b16 v[116:117], v139 offset:0xa00
	v_mfma_f32_32x32x16_bf16 v[0:15], v[102:105], v[118:121], v[0:15]
	ds_read_b64_tr_b16 v[118:119], v139 offset:0x1200
	ds_read_b64_tr_b16 v[120:121], v139 offset:0x1a00
	v_mfma_f32_32x32x16_bf16 v[0:15], v[106:109], v[126:129], v[0:15]
	ds_read_b64_tr_b16 v[126:127], v139 offset:0x2200
	ds_read_b64_tr_b16 v[128:129], v139 offset:0x2a00
	v_mfma_f32_32x32x16_bf16 v[0:15], v[110:113], v[130:133], v[0:15]
	ds_read_b64_tr_b16 v[130:131], v139 offset:0x3200
	ds_read_b64_tr_b16 v[132:133], v139 offset:0x3a00
	s_waitcnt lgkmcnt(0)
; #define SBAR() __builtin_amdgcn_sched_barrier(0)
; template <int D0> DEVI void pv_one(f32x16& od, int vb, bf16x8 pa0, bf16x8 pa1, bf16x8 pa2, bf16x8 pa3) {
;   const s16x4 l0 = tr_read<v_rd_off(D0, 0, 0)>(vb), h0 = tr_read<v_rd_off(D0, 0, 1)>(vb), l1 = tr_read<v_rd_off(D0, 1, 0)>(vb), h1 = tr_read<v_rd_off(D0, 1, 1)>(vb);
;   const s16x4 l2 = tr_read<v_rd_off(D0, 2, 0)>(vb), h2 = tr_read<v_rd_off(D0, 2, 1)>(vb), l3 = tr_read<v_rd_off(D0, 3, 0)>(vb), h3 = tr_read<v_rd_off(D0, 3, 1)>(vb);
;   asm volatile("s_waitcnt lgkmcnt(0)" ::: "memory"); SBAR();
;     ...
;   od = __builtin_amdgcn_mfma_f32_32x32x16_bf16(pa0, PK(l0, h0), od, 0, 0, 0);
;   od = __builtin_amdgcn_mfma_f32_32x32x16_bf16(pa1, PK(l1, h1), od, 0, 0, 0);
;   od = __builtin_amdgcn_mfma_f32_32x32x16_bf16(pa2, PK(l2, h2), od, 0, 0, 0);
;   od = __builtin_amdgcn_mfma_f32_32x32x16_bf16(pa3, PK(l3, h3), od, 0, 0, 0);
;     ...
; }
; DEVI void pv_d0(f32x16* o, int vb, bf16x8 pa0, bf16x8 pa1, bf16x8 pa2, bf16x8 pa3) {
;   pv_one<0>(o[0], vb, pa0, pa1, pa2, pa3); pv_one<1>(o[1], vb, pa0, pa1, pa2, pa3); pv_one<2>(o[2], vb, pa0, pa1, pa2, pa3); pv_one<3>(o[3], vb, pa0, pa1, pa2, pa3);
; }
; DEVI void partialSM(f32x16& p0, f32x16& p1, float& m_reg, float& mn, float& alpha, float scale) {
;   const float C = scale * 1.4426950408889634f;
;   float pmax = p0[0];
; #pragma unroll
;   for (int r = 1; r < 16; ++r) pmax = fmaxf(pmax, p0[r]);
; #pragma unroll
;   for (int r = 0; r < 16; ++r) pmax = fmaxf(pmax, p1[r]);
;   { auto rr = __builtin_amdgcn_permlane32_swap(__float_as_uint(pmax), __float_as_uint(pmax), false, false);
;     pmax = fmaxf(__uint_as_float(rr[0]), __uint_as_float(rr[1])); }
;   if (__builtin_expect(__all(pmax - m_reg <= ATT_THR / scale), 1)) { mn = m_reg; alpha = 1.f; }
;   else { mn = fmaxf(m_reg, pmax); alpha = __builtin_amdgcn_exp2f((m_reg - mn) * C); m_reg = mn; }
	v_mfma_f32_32x32x16_bf16 v[48:63], v[98:101], v[114:117], v[48:63]
	ds_read_b64_tr_b16 v[114:115], v139 offset:0x400
	ds_read_b64_tr_b16 v[116:117], v139 offset:0xc00
	v_mfma_f32_32x32x16_bf16 v[48:63], v[102:105], v[118:121], v[48:63]
	ds_read_b64_tr_b16 v[118:119], v139 offset:0x1400
	ds_read_b64_tr_b16 v[120:121], v139 offset:0x1c00
	v_mfma_f32_32x32x16_bf16 v[48:63], v[106:109], v[126:129], v[48:63]
	ds_read_b64_tr_b16 v[126:127], v139 offset:0x2400
	ds_read_b64_tr_b16 v[128:129], v139 offset:0x2c00
	v_mfma_f32_32x32x16_bf16 v[48:63], v[110:113], v[130:133], v[48:63]
	ds_read_b64_tr_b16 v[130:131], v139 offset:0x3400
	ds_read_b64_tr_b16 v[132:133], v139 offset:0x3c00
	s_waitcnt lgkmcnt(0)
	v_mfma_f32_32x32x16_bf16 v[32:47], v[98:101], v[114:117], v[32:47]
	ds_read_b64_tr_b16 v[114:115], v139 offset:0x600
	ds_read_b64_tr_b16 v[116:117], v139 offset:0xe00
	v_mfma_f32_32x32x16_bf16 v[32:47], v[102:105], v[118:121], v[32:47]
	ds_read_b64_tr_b16 v[118:119], v139 offset:0x1600
	ds_read_b64_tr_b16 v[120:121], v139 offset:0x1e00
	v_mfma_f32_32x32x16_bf16 v[32:47], v[106:109], v[126:129], v[32:47]
	ds_read_b64_tr_b16 v[126:127], v139 offset:0x2600
	ds_read_b64_tr_b16 v[128:129], v139 offset:0x2e00
	v_mfma_f32_32x32x16_bf16 v[32:47], v[110:113], v[130:133], v[32:47]
	ds_read_b64_tr_b16 v[130:131], v139 offset:0x3600
	ds_read_b64_tr_b16 v[132:133], v139 offset:0x3e00
	s_waitcnt lgkmcnt(0)
	v_mfma_f32_32x32x16_bf16 v[16:31], v[98:101], v[114:117], v[16:31]
	v_max_f32_e32 v98, v81, v81
	v_max_f32_e32 v99, v80, v80
	v_max_f32_e32 v98, v99, v98
	v_max3_f32 v98, v98, v82, v83
	v_max3_f32 v98, v98, v84, v85
	v_max3_f32 v98, v98, v86, v87
	v_max3_f32 v98, v98, v88, v89
	v_max3_f32 v98, v98, v90, v91
	v_max3_f32 v98, v98, v92, v93
	v_mfma_f32_32x32x16_bf16 v[16:31], v[102:105], v[118:121], v[16:31]
	v_max3_f32 v98, v98, v94, v95
	v_max3_f32 v98, v98, v64, v65
	v_max3_f32 v98, v98, v66, v67
	v_max3_f32 v98, v98, v68, v69
	v_max3_f32 v98, v98, v70, v71
	v_max3_f32 v98, v98, v72, v73
	v_max3_f32 v98, v98, v74, v75
	v_max3_f32 v98, v98, v76, v77
	v_mfma_f32_32x32x16_bf16 v[16:31], v[106:109], v[126:129], v[16:31]
	v_max3_f32 v98, v98, v78, v79
	v_mov_b32_e32 v99, v98
	s_nop 1
	v_permlane32_swap_b32_e32 v98, v99
	v_max_f32_e32 v99, v99, v99
	v_max_f32_e32 v98, v98, v98
	v_max_f32_e32 v98, v98, v99
	v_sub_f32_e32 v99, v98, v148
	v_cmp_ge_f32_e32 vcc, s64, v99
	v_max_f32_e32 v99, v148, v148
	v_max_f32_e32 v99, v99, v98
	v_mfma_f32_32x32x16_bf16 v[16:31], v[110:113], v[130:133], v[16:31]
	v_sub_f32_e32 v98, v148, v99
	v_mul_f32_e32 v98, 0x3e38aa3b, v98
	v_exp_f32_e32 v98, v98
	s_cmp_eq_u64 vcc, exec
	s_cselect_b64 s[8:9], -1, 0
	v_cndmask_b32_e64 v98, v98, 1.0, s[8:9]
	v_cmp_gt_f32_e32 vcc, 1.0, v98
	s_barrier
	s_cbranch_vccz .LBB0_483
	s_and_saveexec_b64 s[10:11], s[6:7]
	ds_write_b32 v136, v98 offset:49280
	s_or_b64 exec, exec, s[10:11]
	s_waitcnt lgkmcnt(0)
	v_add_u32_e32 v112, v125, v192
	ds_read_b128 v[100:103], v112 offset:49376
	ds_read_b128 v[104:107], v112 offset:49344
	ds_read_b128 v[108:111], v112 offset:49312
	ds_read_b128 v[112:115], v112 offset:49280
	s_waitcnt lgkmcnt(3)
	v_pk_mul_f32 v[12:13], v[12:13], v[100:101]
	s_waitcnt lgkmcnt(2)
	v_pk_mul_f32 v[8:9], v[8:9], v[104:105]
	s_waitcnt lgkmcnt(1)
	v_pk_mul_f32 v[4:5], v[4:5], v[108:109]
	v_pk_mul_f32 v[14:15], v[14:15], v[102:103]
	v_pk_mul_f32 v[10:11], v[10:11], v[106:107]
	v_pk_mul_f32 v[6:7], v[6:7], v[110:111]
	s_waitcnt lgkmcnt(0)
	v_pk_mul_f32 v[2:3], v[2:3], v[114:115]
	v_pk_mul_f32 v[0:1], v[0:1], v[112:113]
	v_pk_mul_f32 v[60:61], v[60:61], v[100:101]
	v_pk_mul_f32 v[56:57], v[56:57], v[104:105]
	v_pk_mul_f32 v[52:53], v[52:53], v[108:109]
	v_pk_mul_f32 v[62:63], v[62:63], v[102:103]
	v_pk_mul_f32 v[58:59], v[58:59], v[106:107]
	v_pk_mul_f32 v[54:55], v[54:55], v[110:111]
	v_pk_mul_f32 v[50:51], v[50:51], v[114:115]
	v_pk_mul_f32 v[48:49], v[48:49], v[112:113]
	v_pk_mul_f32 v[44:45], v[44:45], v[100:101]
	v_pk_mul_f32 v[40:41], v[40:41], v[104:105]
	v_pk_mul_f32 v[36:37], v[36:37], v[108:109]
	v_pk_mul_f32 v[46:47], v[46:47], v[102:103]
	v_pk_mul_f32 v[42:43], v[42:43], v[106:107]
	v_pk_mul_f32 v[38:39], v[38:39], v[110:111]
	v_pk_mul_f32 v[34:35], v[34:35], v[114:115]
	v_pk_mul_f32 v[32:33], v[32:33], v[112:113]
	v_pk_mul_f32 v[28:29], v[28:29], v[100:101]
	v_pk_mul_f32 v[24:25], v[24:25], v[104:105]
	v_pk_mul_f32 v[20:21], v[20:21], v[108:109]
	v_pk_mul_f32 v[30:31], v[30:31], v[102:103]
	v_pk_mul_f32 v[26:27], v[26:27], v[106:107]
	v_pk_mul_f32 v[22:23], v[22:23], v[110:111]
	v_pk_mul_f32 v[18:19], v[18:19], v[114:115]
	v_pk_mul_f32 v[16:17], v[16:17], v[112:113]
